# v26 + memory-attention PV GEMM epilogue: 7 per-row rsum loads hoisted (no store-inclusive vmcnt waits)
# speedup vs baseline: 1.0018x; 1.0018x over previous
; __device__ __forceinline__ unsigned cvt_pk_bf16(float lo, float hi) { unsigned r; asm volatile("v_cvt_pk_bf16_f32 %0, %1, %2" : "=v"(r) : "v"(lo), "v"(hi)); return r; }
;     __device__ __forceinline__ void operator()(f32x4 (&acc)[2][2][4][2], const Unit& u, int wr, int wc, int fr, int fq) const {
;         const int row0 = u.orow + wr * 64 + fr, col0 = u.ocol + wc * 32 + 8 * fq;
; #pragma unroll
;         for (int ai = 0; ai < 2; ++ai)
; #pragma unroll
;             for (int m = 0; m < 4; ++m) { const int row = row0 + ai * HALF + m * 16; bf16_t* rowp = O + (size_t)row * DM + col0;
;                 const f32x4 ps = *(const f32x4*)(rsum + ((size_t)row * 4 + u.aux) * 4); const float inv = 1.0f / ((ps[0] + ps[1]) + (ps[2] + ps[3]));
; #pragma unroll
;                 for (int bj = 0; bj < 2; ++bj) { const f32x4 v0 = acc[ai][bj][m][0] * inv, v1 = acc[ai][bj][m][1] * inv;
;                     u32x4 w; w.x = cvt_pk_bf16(v0[0], v0[1]); w.y = cvt_pk_bf16(v0[2], v0[3]); w.z = cvt_pk_bf16(v1[0], v1[1]); w.w = cvt_pk_bf16(v1[2], v1[3]);
;                     *(u32x4*)(rowp + bj * HALF) = w; } }
;     }
.LBB0_770:
	v_add_u32_e32 v130, s0, v137
	v_add_u32_e32 v132, s1, v138
	v_ashrrev_i32_e32 v131, 31, v130
	v_ashrrev_i32_e32 v133, 31, v132
	v_lshlrev_b64 v[142:143], 12, v[130:131]
	v_lshl_add_u64 v[142:143], s[78:79], 0, v[142:143]
	v_lshlrev_b64 v[132:133], 1, v[132:133]
	v_lshl_add_u64 v[146:147], v[142:143], 0, v[132:133]
	s_ashr_i32 s27, s26, 31
	v_lshlrev_b64 v[142:143], 6, v[130:131]
	v_lshl_add_u64 v[142:143], s[24:25], 0, v[142:143]
	s_lshl_b64 s[58:59], s[26:27], 4
	v_lshl_add_u64 v[142:143], v[142:143], 0, s[58:59]
	v_add_co_u32_e32 v198, vcc, 0x2000, v142
	s_nop 1
	v_addc_co_u32_e32 v199, vcc, 0, v143, vcc
	global_load_dwordx4 v[152:155], v[142:143], off offset:1024
	global_load_dwordx4 v[156:159], v[142:143], off offset:2048
	global_load_dwordx4 v[160:163], v[142:143], off offset:3072
	global_load_dwordx4 v[164:167], v[198:199], off
	global_load_dwordx4 v[168:171], v[198:199], off offset:1024
	global_load_dwordx4 v[172:175], v[198:199], off offset:2048
	global_load_dwordx4 v[194:197], v[198:199], off offset:3072
	global_load_dwordx4 v[142:145], v[142:143], off
	v_readlane_b32 s16, v254, 33
	s_mov_b64 s[2:3], -1
	v_readlane_b32 s17, v254, 34
	s_waitcnt vmcnt(0)
	v_mov_b32_e32 v148, v143
	v_mov_b32_e32 v149, v144
	v_mov_b32_e32 v143, v145
	v_pk_add_f32 v[142:143], v[148:149], v[142:143]
	s_nop 0
	v_add_f32_e32 v131, v142, v143
	v_div_scale_f32 v141, s[0:1], v131, v131, 1.0
	v_rcp_f32_e32 v142, v141
	s_nop 0
	v_fma_f32 v143, -v141, v142, 1.0
	v_fmac_f32_e32 v142, v143, v142
	v_div_scale_f32 v143, vcc, 1.0, v131, 1.0
	v_mul_f32_e32 v144, v143, v142
	v_fma_f32 v145, -v141, v144, v143
	v_fmac_f32_e32 v144, v145, v142
	v_fma_f32 v141, -v141, v144, v143
	v_div_fmas_f32 v141, v141, v142, v144
	v_div_fixup_f32 v142, v141, v131, 1.0
	v_pk_mul_f32 v[114:115], v[114:115], v[142:143] op_sel_hi:[1,0]
	v_pk_mul_f32 v[116:117], v[116:117], v[142:143] op_sel_hi:[1,0]
	v_cvt_pk_bf16_f32 v114, v114, v115
	v_pk_mul_f32 v[120:121], v[120:121], v[142:143] op_sel_hi:[1,0]
	v_cvt_pk_bf16_f32 v115, v116, v117
	v_pk_mul_f32 v[118:119], v[118:119], v[142:143] op_sel_hi:[1,0]
	s_nop 0
	v_cvt_pk_bf16_f32 v116, v118, v119
	v_cvt_pk_bf16_f32 v117, v120, v121
	global_store_dwordx4 v[146:147], v[114:117], off
	v_pk_mul_f32 v[118:119], v[128:129], v[142:143] op_sel_hi:[1,0]
	v_pk_mul_f32 v[120:121], v[126:127], v[142:143] op_sel_hi:[1,0]
	v_pk_mul_f32 v[114:115], v[122:123], v[142:143] op_sel_hi:[1,0]
	v_pk_mul_f32 v[116:117], v[124:125], v[142:143] op_sel_hi:[1,0]
	v_cvt_pk_bf16_f32 v114, v114, v115
	s_nop 0
	v_cvt_pk_bf16_f32 v115, v116, v117
	v_cvt_pk_bf16_f32 v116, v120, v121
	v_cvt_pk_bf16_f32 v117, v118, v119
	global_store_dwordx4 v[146:147], v[114:117], off offset:256
	s_nop 1
	v_add_u32_e32 v114, 16, v130
	v_ashrrev_i32_e32 v115, 31, v114
	v_lshlrev_b64 v[116:117], 12, v[114:115]
	v_lshlrev_b64 v[114:115], 6, v[114:115]
	v_lshl_add_u64 v[114:115], s[24:25], 0, v[114:115]
	v_lshl_add_u64 v[116:117], s[78:79], 0, v[116:117]
	v_lshl_add_u64 v[114:115], v[114:115], 0, s[58:59]
	v_lshl_add_u64 v[118:119], v[116:117], 0, v[132:133]
	v_mov_b32_e32 v114, v152
	v_mov_b32_e32 v115, v153
	v_mov_b32_e32 v116, v154
	v_mov_b32_e32 v117, v155
	v_mov_b32_e32 v120, v115
	v_mov_b32_e32 v121, v116
	v_mov_b32_e32 v115, v117
	v_pk_add_f32 v[114:115], v[120:121], v[114:115]
	s_nop 0
	v_add_f32_e32 v114, v114, v115
	v_div_scale_f32 v115, s[0:1], v114, v114, 1.0
	v_rcp_f32_e32 v116, v115
	s_nop 0
	v_fma_f32 v117, -v115, v116, 1.0
	v_fmac_f32_e32 v116, v117, v116
	v_div_scale_f32 v117, vcc, 1.0, v114, 1.0
	v_mul_f32_e32 v120, v117, v116
	v_fma_f32 v121, -v115, v120, v117
	v_fmac_f32_e32 v120, v121, v116
	v_fma_f32 v115, -v115, v120, v117
	v_div_fmas_f32 v115, v115, v116, v120
	v_div_fixup_f32 v114, v115, v114, 1.0
	v_pk_mul_f32 v[98:99], v[98:99], v[114:115] op_sel_hi:[1,0]
	v_pk_mul_f32 v[100:101], v[100:101], v[114:115] op_sel_hi:[1,0]
	v_cvt_pk_bf16_f32 v98, v98, v99
	v_pk_mul_f32 v[104:105], v[104:105], v[114:115] op_sel_hi:[1,0]
	v_cvt_pk_bf16_f32 v99, v100, v101
	v_pk_mul_f32 v[102:103], v[102:103], v[114:115] op_sel_hi:[1,0]
	s_nop 0
	v_cvt_pk_bf16_f32 v100, v102, v103
	v_cvt_pk_bf16_f32 v101, v104, v105
	global_store_dwordx4 v[118:119], v[98:101], off
	v_pk_mul_f32 v[102:103], v[112:113], v[114:115] op_sel_hi:[1,0]
	v_pk_mul_f32 v[104:105], v[110:111], v[114:115] op_sel_hi:[1,0]
	v_pk_mul_f32 v[98:99], v[106:107], v[114:115] op_sel_hi:[1,0]
	v_pk_mul_f32 v[100:101], v[108:109], v[114:115] op_sel_hi:[1,0]
	v_cvt_pk_bf16_f32 v98, v98, v99
	s_nop 0
	v_cvt_pk_bf16_f32 v99, v100, v101
	v_cvt_pk_bf16_f32 v100, v104, v105
	v_cvt_pk_bf16_f32 v101, v102, v103
	global_store_dwordx4 v[118:119], v[98:101], off offset:256
	s_nop 1
	v_add_u32_e32 v98, 32, v130
	v_ashrrev_i32_e32 v99, 31, v98
	v_lshlrev_b64 v[100:101], 12, v[98:99]
	v_lshlrev_b64 v[98:99], 6, v[98:99]
	v_lshl_add_u64 v[98:99], s[24:25], 0, v[98:99]
	v_lshl_add_u64 v[100:101], s[78:79], 0, v[100:101]
	v_lshl_add_u64 v[98:99], v[98:99], 0, s[58:59]
	v_lshl_add_u64 v[102:103], v[100:101], 0, v[132:133]
	v_mov_b32_e32 v98, v156
	v_mov_b32_e32 v99, v157
	v_mov_b32_e32 v100, v158
	v_mov_b32_e32 v101, v159
	v_mov_b32_e32 v104, v99
	v_mov_b32_e32 v105, v100
	v_mov_b32_e32 v99, v101
	v_pk_add_f32 v[98:99], v[104:105], v[98:99]
	s_nop 0
	v_add_f32_e32 v98, v98, v99
	v_div_scale_f32 v99, s[0:1], v98, v98, 1.0
	v_rcp_f32_e32 v100, v99
	s_nop 0
	v_fma_f32 v101, -v99, v100, 1.0
	v_fmac_f32_e32 v100, v101, v100
	v_div_scale_f32 v101, vcc, 1.0, v98, 1.0
	v_mul_f32_e32 v104, v101, v100
	v_fma_f32 v105, -v99, v104, v101
	v_fmac_f32_e32 v104, v105, v100
	v_fma_f32 v99, -v99, v104, v101
	v_div_fmas_f32 v99, v99, v100, v104
; __device__ __forceinline__ unsigned cvt_pk_bf16(float lo, float hi) { unsigned r; asm volatile("v_cvt_pk_bf16_f32 %0, %1, %2" : "=v"(r) : "v"(lo), "v"(hi)); return r; }
;     __device__ __forceinline__ void operator()(f32x4 (&acc)[2][2][4][2], const Unit& u, int wr, int wc, int fr, int fq) const {
;         const int row0 = u.orow + wr * 64 + fr, col0 = u.ocol + wc * 32 + 8 * fq;
; #pragma unroll
;         for (int ai = 0; ai < 2; ++ai)
; #pragma unroll
;             for (int m = 0; m < 4; ++m) { const int row = row0 + ai * HALF + m * 16; bf16_t* rowp = O + (size_t)row * DM + col0;
;                 const f32x4 ps = *(const f32x4*)(rsum + ((size_t)row * 4 + u.aux) * 4); const float inv = 1.0f / ((ps[0] + ps[1]) + (ps[2] + ps[3]));
; #pragma unroll
;                 for (int bj = 0; bj < 2; ++bj) { const f32x4 v0 = acc[ai][bj][m][0] * inv, v1 = acc[ai][bj][m][1] * inv;
;                     u32x4 w; w.x = cvt_pk_bf16(v0[0], v0[1]); w.y = cvt_pk_bf16(v0[2], v0[3]); w.z = cvt_pk_bf16(v1[0], v1[1]); w.w = cvt_pk_bf16(v1[2], v1[3]);
;                     *(u32x4*)(rowp + bj * HALF) = w; } }
	v_div_fixup_f32 v98, v99, v98, 1.0
	v_pk_mul_f32 v[82:83], v[82:83], v[98:99] op_sel_hi:[1,0]
	v_pk_mul_f32 v[84:85], v[84:85], v[98:99] op_sel_hi:[1,0]
	v_cvt_pk_bf16_f32 v82, v82, v83
	v_pk_mul_f32 v[88:89], v[88:89], v[98:99] op_sel_hi:[1,0]
	v_cvt_pk_bf16_f32 v83, v84, v85
	v_pk_mul_f32 v[86:87], v[86:87], v[98:99] op_sel_hi:[1,0]
	s_nop 0
	v_cvt_pk_bf16_f32 v84, v86, v87
	v_cvt_pk_bf16_f32 v85, v88, v89
	global_store_dwordx4 v[102:103], v[82:85], off
	v_pk_mul_f32 v[86:87], v[96:97], v[98:99] op_sel_hi:[1,0]
	v_pk_mul_f32 v[88:89], v[94:95], v[98:99] op_sel_hi:[1,0]
	v_pk_mul_f32 v[82:83], v[90:91], v[98:99] op_sel_hi:[1,0]
	v_pk_mul_f32 v[84:85], v[92:93], v[98:99] op_sel_hi:[1,0]
	v_cvt_pk_bf16_f32 v82, v82, v83
	s_nop 0
	v_cvt_pk_bf16_f32 v83, v84, v85
	v_cvt_pk_bf16_f32 v84, v88, v89
	v_cvt_pk_bf16_f32 v85, v86, v87
	global_store_dwordx4 v[102:103], v[82:85], off offset:256
	s_nop 1
	v_add_u32_e32 v82, 48, v130
	v_ashrrev_i32_e32 v83, 31, v82
	v_lshlrev_b64 v[84:85], 12, v[82:83]
	v_lshlrev_b64 v[82:83], 6, v[82:83]
	v_lshl_add_u64 v[82:83], s[24:25], 0, v[82:83]
	v_lshl_add_u64 v[84:85], s[78:79], 0, v[84:85]
	v_lshl_add_u64 v[82:83], v[82:83], 0, s[58:59]
	v_lshl_add_u64 v[86:87], v[84:85], 0, v[132:133]
	v_mov_b32_e32 v82, v160
	v_mov_b32_e32 v83, v161
	v_mov_b32_e32 v84, v162
	v_mov_b32_e32 v85, v163
	v_mov_b32_e32 v88, v83
	v_mov_b32_e32 v89, v84
	v_mov_b32_e32 v83, v85
	v_pk_add_f32 v[82:83], v[88:89], v[82:83]
	s_nop 0
	v_add_f32_e32 v82, v82, v83
	v_div_scale_f32 v83, s[0:1], v82, v82, 1.0
	v_rcp_f32_e32 v84, v83
	s_nop 0
	v_fma_f32 v85, -v83, v84, 1.0
	v_fmac_f32_e32 v84, v85, v84
	v_div_scale_f32 v85, vcc, 1.0, v82, 1.0
	v_mul_f32_e32 v88, v85, v84
	v_fma_f32 v89, -v83, v88, v85
	v_fmac_f32_e32 v88, v89, v84
	v_fma_f32 v83, -v83, v88, v85
	v_div_fmas_f32 v83, v83, v84, v88
	v_div_fixup_f32 v82, v83, v82, 1.0
	v_pk_mul_f32 v[66:67], v[66:67], v[82:83] op_sel_hi:[1,0]
	v_pk_mul_f32 v[68:69], v[68:69], v[82:83] op_sel_hi:[1,0]
	v_cvt_pk_bf16_f32 v66, v66, v67
	v_pk_mul_f32 v[72:73], v[72:73], v[82:83] op_sel_hi:[1,0]
	v_cvt_pk_bf16_f32 v67, v68, v69
	v_pk_mul_f32 v[70:71], v[70:71], v[82:83] op_sel_hi:[1,0]
	s_nop 0
	v_cvt_pk_bf16_f32 v68, v70, v71
	v_cvt_pk_bf16_f32 v69, v72, v73
	global_store_dwordx4 v[86:87], v[66:69], off
	v_pk_mul_f32 v[70:71], v[80:81], v[82:83] op_sel_hi:[1,0]
	v_pk_mul_f32 v[72:73], v[78:79], v[82:83] op_sel_hi:[1,0]
	v_pk_mul_f32 v[66:67], v[74:75], v[82:83] op_sel_hi:[1,0]
	v_pk_mul_f32 v[68:69], v[76:77], v[82:83] op_sel_hi:[1,0]
	v_cvt_pk_bf16_f32 v66, v66, v67
	s_nop 0
	v_cvt_pk_bf16_f32 v67, v68, v69
	v_cvt_pk_bf16_f32 v68, v72, v73
	v_cvt_pk_bf16_f32 v69, v70, v71
	global_store_dwordx4 v[86:87], v[66:69], off offset:256
	s_nop 1
	v_add_u32_e32 v66, 0x80, v130
	v_ashrrev_i32_e32 v67, 31, v66
	v_lshlrev_b64 v[68:69], 12, v[66:67]
	v_lshlrev_b64 v[66:67], 6, v[66:67]
	v_lshl_add_u64 v[66:67], s[24:25], 0, v[66:67]
	v_lshl_add_u64 v[68:69], s[78:79], 0, v[68:69]
	v_lshl_add_u64 v[66:67], v[66:67], 0, s[58:59]
	v_lshl_add_u64 v[70:71], v[68:69], 0, v[132:133]
	v_mov_b32_e32 v66, v164
	v_mov_b32_e32 v67, v165
	v_mov_b32_e32 v68, v166
	v_mov_b32_e32 v69, v167
	v_mov_b32_e32 v72, v67
	v_mov_b32_e32 v73, v68
	v_mov_b32_e32 v67, v69
	v_pk_add_f32 v[66:67], v[72:73], v[66:67]
	s_nop 0
	v_add_f32_e32 v66, v66, v67
	v_div_scale_f32 v67, s[0:1], v66, v66, 1.0
	v_rcp_f32_e32 v68, v67
	s_nop 0
	v_fma_f32 v69, -v67, v68, 1.0
	v_fmac_f32_e32 v68, v69, v68
	v_div_scale_f32 v69, vcc, 1.0, v66, 1.0
	v_mul_f32_e32 v72, v69, v68
	v_fma_f32 v73, -v67, v72, v69
	v_fmac_f32_e32 v72, v73, v68
	v_fma_f32 v67, -v67, v72, v69
	v_div_fmas_f32 v67, v67, v68, v72
	v_div_fixup_f32 v66, v67, v66, 1.0
	v_pk_mul_f32 v[50:51], v[50:51], v[66:67] op_sel_hi:[1,0]
	v_pk_mul_f32 v[52:53], v[52:53], v[66:67] op_sel_hi:[1,0]
	v_cvt_pk_bf16_f32 v50, v50, v51
	v_pk_mul_f32 v[56:57], v[56:57], v[66:67] op_sel_hi:[1,0]
	v_cvt_pk_bf16_f32 v51, v52, v53
	v_pk_mul_f32 v[54:55], v[54:55], v[66:67] op_sel_hi:[1,0]
	s_nop 0
	v_cvt_pk_bf16_f32 v52, v54, v55
	v_cvt_pk_bf16_f32 v53, v56, v57
	global_store_dwordx4 v[70:71], v[50:53], off
	v_pk_mul_f32 v[54:55], v[64:65], v[66:67] op_sel_hi:[1,0]
	v_pk_mul_f32 v[56:57], v[62:63], v[66:67] op_sel_hi:[1,0]
	v_pk_mul_f32 v[50:51], v[58:59], v[66:67] op_sel_hi:[1,0]
	v_pk_mul_f32 v[52:53], v[60:61], v[66:67] op_sel_hi:[1,0]
	v_cvt_pk_bf16_f32 v50, v50, v51
	s_nop 0
	v_cvt_pk_bf16_f32 v51, v52, v53
	v_cvt_pk_bf16_f32 v52, v56, v57
	v_cvt_pk_bf16_f32 v53, v54, v55
	global_store_dwordx4 v[70:71], v[50:53], off offset:256
	s_nop 1
	v_add_u32_e32 v50, 0x90, v130
	v_ashrrev_i32_e32 v51, 31, v50
	v_lshlrev_b64 v[52:53], 12, v[50:51]
	v_lshlrev_b64 v[50:51], 6, v[50:51]
	v_lshl_add_u64 v[50:51], s[24:25], 0, v[50:51]
	v_lshl_add_u64 v[52:53], s[78:79], 0, v[52:53]
	v_lshl_add_u64 v[50:51], v[50:51], 0, s[58:59]
	v_lshl_add_u64 v[54:55], v[52:53], 0, v[132:133]
	v_mov_b32_e32 v50, v168
	v_mov_b32_e32 v51, v169
	v_mov_b32_e32 v52, v170
	v_mov_b32_e32 v53, v171
	v_mov_b32_e32 v56, v51
	v_mov_b32_e32 v57, v52
	v_mov_b32_e32 v51, v53
	v_pk_add_f32 v[50:51], v[56:57], v[50:51]
; __device__ __forceinline__ unsigned cvt_pk_bf16(float lo, float hi) { unsigned r; asm volatile("v_cvt_pk_bf16_f32 %0, %1, %2" : "=v"(r) : "v"(lo), "v"(hi)); return r; }
; #define PG8_BAR __builtin_amdgcn_s_barrier()
;     __device__ __forceinline__ void operator()(f32x4 (&acc)[2][2][4][2], const Unit& u, int wr, int wc, int fr, int fq) const {
;         const int row0 = u.orow + wr * 64 + fr, col0 = u.ocol + wc * 32 + 8 * fq;
; #pragma unroll
;         for (int ai = 0; ai < 2; ++ai)
; #pragma unroll
;             for (int m = 0; m < 4; ++m) { const int row = row0 + ai * HALF + m * 16; bf16_t* rowp = O + (size_t)row * DM + col0;
;                 const f32x4 ps = *(const f32x4*)(rsum + ((size_t)row * 4 + u.aux) * 4); const float inv = 1.0f / ((ps[0] + ps[1]) + (ps[2] + ps[3]));
; #pragma unroll
;                 for (int bj = 0; bj < 2; ++bj) { const f32x4 v0 = acc[ai][bj][m][0] * inv, v1 = acc[ai][bj][m][1] * inv;
;                     u32x4 w; w.x = cvt_pk_bf16(v0[0], v0[1]); w.y = cvt_pk_bf16(v0[2], v0[3]); w.z = cvt_pk_bf16(v1[0], v1[1]); w.w = cvt_pk_bf16(v1[2], v1[3]);
;                     *(u32x4*)(rowp + bj * HALF) = w; } }
; template <class Epi, class Sched>
; __device__ __forceinline__ void gemm_phase(LAS unsigned char* lds, const Gemm g, const Sched& S, const Epi& E, int wave_id) {
;     ...
;         E(acc, cur, wr, wc, fr, fq);
;         if (!has_next) break;
; #pragma unroll
;         for (int a = 0; a < 2; ++a)
; #pragma unroll
;             for (int b = 0; b < 2; ++b)
; #pragma unroll
;                 for (int m = 0; m < 4; ++m)
; #pragma unroll
;                     for (int n = 0; n < 2; ++n) acc[a][b][m][n] = (f32x4){0.f, 0.f, 0.f, 0.f};
;         cur = nxt; cA = nA; cB = nB; ++ui;
;         if (wr == 1) PG8_BAR;
	s_nop 0
	v_add_f32_e32 v50, v50, v51
	v_div_scale_f32 v51, s[0:1], v50, v50, 1.0
	v_rcp_f32_e32 v52, v51
	s_nop 0
	v_fma_f32 v53, -v51, v52, 1.0
	v_fmac_f32_e32 v52, v53, v52
	v_div_scale_f32 v53, vcc, 1.0, v50, 1.0
	v_mul_f32_e32 v56, v53, v52
	v_fma_f32 v57, -v51, v56, v53
	v_fmac_f32_e32 v56, v57, v52
	v_fma_f32 v51, -v51, v56, v53
	v_div_fmas_f32 v51, v51, v52, v56
	v_div_fixup_f32 v50, v51, v50, 1.0
	v_pk_mul_f32 v[34:35], v[34:35], v[50:51] op_sel_hi:[1,0]
	v_pk_mul_f32 v[36:37], v[36:37], v[50:51] op_sel_hi:[1,0]
	v_cvt_pk_bf16_f32 v34, v34, v35
	v_pk_mul_f32 v[40:41], v[40:41], v[50:51] op_sel_hi:[1,0]
	v_cvt_pk_bf16_f32 v35, v36, v37
	v_pk_mul_f32 v[38:39], v[38:39], v[50:51] op_sel_hi:[1,0]
	s_nop 0
	v_cvt_pk_bf16_f32 v36, v38, v39
	v_cvt_pk_bf16_f32 v37, v40, v41
	global_store_dwordx4 v[54:55], v[34:37], off
	v_pk_mul_f32 v[38:39], v[48:49], v[50:51] op_sel_hi:[1,0]
	v_pk_mul_f32 v[40:41], v[46:47], v[50:51] op_sel_hi:[1,0]
	v_pk_mul_f32 v[34:35], v[42:43], v[50:51] op_sel_hi:[1,0]
	v_pk_mul_f32 v[36:37], v[44:45], v[50:51] op_sel_hi:[1,0]
	v_cvt_pk_bf16_f32 v34, v34, v35
	s_nop 0
	v_cvt_pk_bf16_f32 v35, v36, v37
	v_cvt_pk_bf16_f32 v36, v40, v41
	v_cvt_pk_bf16_f32 v37, v38, v39
	global_store_dwordx4 v[54:55], v[34:37], off offset:256
	s_nop 1
	v_add_u32_e32 v34, 0xa0, v130
	v_ashrrev_i32_e32 v35, 31, v34
	v_lshlrev_b64 v[36:37], 12, v[34:35]
	v_lshlrev_b64 v[34:35], 6, v[34:35]
	v_lshl_add_u64 v[34:35], s[24:25], 0, v[34:35]
	v_lshl_add_u64 v[36:37], s[78:79], 0, v[36:37]
	v_lshl_add_u64 v[34:35], v[34:35], 0, s[58:59]
	v_lshl_add_u64 v[38:39], v[36:37], 0, v[132:133]
	v_mov_b32_e32 v34, v172
	v_mov_b32_e32 v35, v173
	v_mov_b32_e32 v36, v174
	v_mov_b32_e32 v37, v175
	v_mov_b32_e32 v40, v35
	v_mov_b32_e32 v41, v36
	v_mov_b32_e32 v35, v37
	v_pk_add_f32 v[34:35], v[40:41], v[34:35]
	s_nop 0
	v_add_f32_e32 v34, v34, v35
	v_div_scale_f32 v35, s[0:1], v34, v34, 1.0
	v_rcp_f32_e32 v36, v35
	s_nop 0
	v_fma_f32 v37, -v35, v36, 1.0
	v_fmac_f32_e32 v36, v37, v36
	v_div_scale_f32 v37, vcc, 1.0, v34, 1.0
	v_mul_f32_e32 v40, v37, v36
	v_fma_f32 v41, -v35, v40, v37
	v_fmac_f32_e32 v40, v41, v36
	v_fma_f32 v35, -v35, v40, v37
	v_div_fmas_f32 v35, v35, v36, v40
	v_div_fixup_f32 v34, v35, v34, 1.0
	v_pk_mul_f32 v[18:19], v[18:19], v[34:35] op_sel_hi:[1,0]
	v_pk_mul_f32 v[20:21], v[20:21], v[34:35] op_sel_hi:[1,0]
	v_cvt_pk_bf16_f32 v18, v18, v19
	v_pk_mul_f32 v[24:25], v[24:25], v[34:35] op_sel_hi:[1,0]
	v_cvt_pk_bf16_f32 v19, v20, v21
	v_pk_mul_f32 v[22:23], v[22:23], v[34:35] op_sel_hi:[1,0]
	s_nop 0
	v_cvt_pk_bf16_f32 v20, v22, v23
	v_cvt_pk_bf16_f32 v21, v24, v25
	global_store_dwordx4 v[38:39], v[18:21], off
	v_pk_mul_f32 v[22:23], v[32:33], v[34:35] op_sel_hi:[1,0]
	v_pk_mul_f32 v[24:25], v[30:31], v[34:35] op_sel_hi:[1,0]
	v_pk_mul_f32 v[18:19], v[26:27], v[34:35] op_sel_hi:[1,0]
	v_pk_mul_f32 v[20:21], v[28:29], v[34:35] op_sel_hi:[1,0]
	v_cvt_pk_bf16_f32 v18, v18, v19
	s_nop 0
	v_cvt_pk_bf16_f32 v19, v20, v21
	v_cvt_pk_bf16_f32 v20, v24, v25
	v_cvt_pk_bf16_f32 v21, v22, v23
	global_store_dwordx4 v[38:39], v[18:21], off offset:256
	s_nop 1
	v_add_u32_e32 v18, 0xb0, v130
	v_ashrrev_i32_e32 v19, 31, v18
	v_lshlrev_b64 v[20:21], 12, v[18:19]
	v_lshlrev_b64 v[18:19], 6, v[18:19]
	v_lshl_add_u64 v[18:19], s[24:25], 0, v[18:19]
	v_lshl_add_u64 v[20:21], s[78:79], 0, v[20:21]
	v_lshl_add_u64 v[18:19], v[18:19], 0, s[58:59]
	v_lshl_add_u64 v[22:23], v[20:21], 0, v[132:133]
	v_mov_b32_e32 v18, v194
	v_mov_b32_e32 v19, v195
	v_mov_b32_e32 v20, v196
	v_mov_b32_e32 v21, v197
	v_readlane_b32 s58, v249, 62
	v_readlane_b32 s59, v249, 63
	v_mov_b32_e32 v24, v19
	v_mov_b32_e32 v25, v20
	v_mov_b32_e32 v19, v21
	v_pk_add_f32 v[18:19], v[24:25], v[18:19]
	s_nop 0
	v_add_f32_e32 v18, v18, v19
	v_div_scale_f32 v19, s[0:1], v18, v18, 1.0
	v_rcp_f32_e32 v20, v19
	s_nop 0
	v_fma_f32 v21, -v19, v20, 1.0
	v_fmac_f32_e32 v20, v21, v20
	v_div_scale_f32 v21, vcc, 1.0, v18, 1.0
	v_mul_f32_e32 v24, v21, v20
	v_fma_f32 v25, -v19, v24, v21
	v_fmac_f32_e32 v24, v25, v20
	v_fma_f32 v19, -v19, v24, v21
	v_div_fmas_f32 v19, v19, v20, v24
	v_div_fixup_f32 v18, v19, v18, 1.0
	v_pk_mul_f32 v[4:5], v[4:5], v[18:19] op_sel_hi:[1,0]
	v_pk_mul_f32 v[2:3], v[2:3], v[18:19] op_sel_hi:[1,0]
	v_pk_mul_f32 v[8:9], v[8:9], v[18:19] op_sel_hi:[1,0]
	v_pk_mul_f32 v[6:7], v[6:7], v[18:19] op_sel_hi:[1,0]
	v_cvt_pk_bf16_f32 v2, v2, v3
	v_cvt_pk_bf16_f32 v3, v4, v5
	s_andn2_b64 vcc, exec, s[40:41]
	v_cvt_pk_bf16_f32 v4, v6, v7
	v_cvt_pk_bf16_f32 v5, v8, v9
	global_store_dwordx4 v[22:23], v[2:5], off
	v_pk_mul_f32 v[6:7], v[16:17], v[18:19] op_sel_hi:[1,0]
	v_pk_mul_f32 v[8:9], v[14:15], v[18:19] op_sel_hi:[1,0]
	v_pk_mul_f32 v[4:5], v[12:13], v[18:19] op_sel_hi:[1,0]
	v_pk_mul_f32 v[2:3], v[10:11], v[18:19] op_sel_hi:[1,0]
	s_nop 0
	v_cvt_pk_bf16_f32 v2, v2, v3
	v_cvt_pk_bf16_f32 v3, v4, v5
	v_cvt_pk_bf16_f32 v4, v8, v9
	v_cvt_pk_bf16_f32 v5, v6, v7
	global_store_dwordx4 v[22:23], v[2:5], off offset:256
	s_cbranch_vccnz .LBB0_765
	s_andn2_b64 vcc, exec, s[4:5]
	s_cbranch_vccnz .LBB0_764
	s_barrier
	s_branch .LBB0_764
